# P2 queue: next position pre-claimed at unit start (returning atomic parked in an AGPR) so dequeue latency overlaps the unit; last 256 positions claimed normally
# baseline (speedup 1.0000x reference)
; #define LAS __attribute__((address_space(3)))
; __device__ __forceinline__ unsigned xb_add(unsigned* p, unsigned v) { return __hip_atomic_fetch_add(p, v, __ATOMIC_RELAXED, __HIP_MEMORY_SCOPE_AGENT); }
; __device__ __forceinline__ unsigned xb_xcc_id() { return (unsigned)__builtin_amdgcn_s_getreg((3 << 11) | 20) & 0xFu; }
; __device__ __forceinline__ XcdBarrier xcd_barrier_post(unsigned* bar, volatile LAS unsigned* st) {
;     XcdBarrier b; b.bar = bar; b.x = xb_xcc_id(); b.st = st;
;     if (threadIdx.x == 0) (void)xb_add(&bar[XB_XCNT(b.x)], 1u);
;     return b;
; }
; __global__ void __launch_bounds__(512) hybrid_fwd(Params p) {
;     extern __shared__ __attribute__((aligned(16))) unsigned char lds_raw[];
;     cg::grid_group grid = cg::this_grid();
;     const int G = gridDim.x;
;     if (threadIdx.x < 16) ((LAS unsigned*)lds_raw)[threadIdx.x] = 0u;
;     __syncthreads();
;     const XcdBarrier xbar = xcd_barrier_post((unsigned*)(p.ws + WS_CTL) + 16384, (volatile LAS unsigned*)((LAS unsigned char*)lds_raw + 16));
_Z10hybrid_fwd6Params:
	s_mov_b32 s100, 0
	v_writelane_b32 v247, s100, 43
	s_load_dwordx8 s[4:11], s[0:1], 0x80
	s_load_dwordx4 s[92:95], s[0:1], 0xa0
	s_load_dword s3, s[0:1], 0xb0
	v_and_b32_e32 v229, 0x3ff, v0
	v_cmp_gt_u32_e32 vcc, 16, v229
	s_waitcnt lgkmcnt(0)
	v_writelane_b32 v250, s4, 0
	s_nop 1
	v_writelane_b32 v250, s5, 1
	v_writelane_b32 v250, s6, 2
	v_writelane_b32 v250, s7, 3
	v_writelane_b32 v250, s8, 4
	v_writelane_b32 v250, s9, 5
	v_writelane_b32 v250, s10, 6
	v_writelane_b32 v250, s11, 7
	s_add_u32 s4, s0, 0xa8
	s_addc_u32 s5, s1, 0
	v_writelane_b32 v250, s4, 8
	s_nop 1
	v_writelane_b32 v250, s5, 9
	s_and_saveexec_b64 s[4:5], vcc
	v_lshl_add_u32 v1, v229, 2, 0
	v_mov_b32_e32 v2, 0
	ds_write_b32 v1, v2
	s_or_b64 exec, exec, s[4:5]
	s_load_dwordx16 s[40:55], s[0:1], 0x0
	s_load_dwordx16 s[4:19], s[0:1], 0x40
	s_waitcnt lgkmcnt(0)
	s_barrier
	s_getreg_b32 s0, hwreg(HW_REG_XCC_ID, 0, 4)
	v_writelane_b32 v250, s4, 10
	s_mov_b32 s37, 0
	s_nop 0
	v_writelane_b32 v250, s5, 11
	v_writelane_b32 v250, s6, 12
	v_writelane_b32 v250, s7, 13
	v_writelane_b32 v250, s8, 14
	v_writelane_b32 v250, s9, 15
	v_writelane_b32 v250, s10, 16
	v_writelane_b32 v250, s11, 17
	v_writelane_b32 v250, s12, 18
	v_writelane_b32 v250, s13, 19
	v_writelane_b32 v250, s14, 20
	v_writelane_b32 v250, s15, 21
	v_writelane_b32 v250, s16, 22
	v_writelane_b32 v250, s17, 23
	v_writelane_b32 v250, s18, 24
	v_writelane_b32 v250, s19, 25
	s_add_u32 s12, s92, 0x10000
	s_addc_u32 s13, s93, 0
	s_and_b32 s14, s0, 15
	v_cmp_eq_u32_e64 s[8:9], 0, v229
	s_lshl_b32 s15, s14, 6
	s_and_saveexec_b64 s[0:1], s[8:9]
	s_cbranch_execz .LBB0_5
	s_mov_b64 s[4:5], exec
	v_mbcnt_lo_u32_b32 v1, s4, 0
	v_mbcnt_hi_u32_b32 v1, s5, v1
	v_cmp_eq_u32_e32 vcc, 0, v1
	s_and_b64 s[6:7], exec, vcc
	s_mov_b64 exec, s[6:7]
	s_cbranch_execz .LBB0_5
	s_lshl_b32 s6, s15, 2
	s_bcnt1_i32_b64 s4, s[4:5]
	v_mov_b32_e32 v1, s6
	v_mov_b32_e32 v2, s4
	global_atomic_add v1, v2, s[12:13] offset:1024

; #define MKCTX() Ctx C; size_t z_ = 0; { int t_ = threadIdx.x; asm volatile("" : "+s"(z_), "+v"(t_)); unsigned char* ws_ = p.ws + z_; const float* rb_ = p.in[1] + z_; \
;     C.lds = (LAS unsigned char*)lds_raw + 64; C.tid = t_; C.lane = t_ & 63; C.wave = __builtin_amdgcn_readfirstlane(t_ >> 6); C.relb = rb_; C.ws = ws_; }
; __global__ void __launch_bounds__(512) hybrid_fwd(Params p) {
;     ...
;             MKCTX();
;             unsigned* ctl = (unsigned*)(C.ws + WS_CTL);
;             __syncthreads();
;             if (C.tid == 0) s_unit = (int)atomicAdd(ctl + 64 * (1 + l), 1u);
;             __syncthreads();
.LBB0_317:
	s_mov_b64 s[20:21], 0
	v_mov_b32_e32 v132, v229
	s_add_u32 s64, s92, s20
	s_addc_u32 s65, s93, s21
	v_readfirstlane_b32 s73, v132
	v_cmp_eq_u32_e64 s[38:39], 0, v132
	s_barrier
	s_and_saveexec_b64 s[40:41], s[38:39]
	s_cbranch_execz .LBB0_321
	v_readlane_b32 s19, v247, 43
	s_nop 1
	s_cmp_eq_u32 s19, 0
	s_cbranch_scc1 .Lpc_normal
	s_waitcnt vmcnt(0)
	v_accvgpr_read_b32 v0, a0
	s_nop 1
	ds_write_b32 v193, v0
	s_branch .LBB0_321
.Lpc_normal:
	s_mov_b64 s[44:45], exec
	v_mbcnt_lo_u32_b32 v0, s44, 0
	v_mbcnt_hi_u32_b32 v0, s45, v0
	v_cmp_eq_u32_e32 vcc, 0, v0
	s_and_saveexec_b64 s[42:43], vcc
	s_cbranch_execz .LBB0_320
	s_add_u32 s20, s64, s62
	s_addc_u32 s21, s65, s63
	s_bcnt1_i32_b64 s19, s[44:45]
	v_mov_b32_e32 v1, s19
	global_atomic_add v1, v193, v1, s[20:21] offset:256 sc0

; __global__ void __launch_bounds__(512) hybrid_fwd(Params p) {
;     ...
;             if (C.tid == 0) s_unit = (int)atomicAdd(ctl + 64 * (1 + l), 1u);
;             __syncthreads();
;             const int u = s_unit;
;             __syncthreads();
;             if (u >= 1024 + 1024 + 512) break;
;             const int v2 = u - 512, grpq = v2 >> 7, rq = v2 & 127;
.LBB0_321:
	s_or_b64 exec, exec, s[40:41]
	s_waitcnt lgkmcnt(0)
	s_barrier
	ds_read_b32 v0, v193
	s_movk_i32 s19, 0x9ff
	s_mov_b64 s[40:41], -1
	s_waitcnt lgkmcnt(0)
	s_barrier
	v_cmp_lt_i32_e32 vcc, s19, v0
	v_readfirstlane_b32 s74, v0
	s_cmp_lt_u32 s74, 0x900
	s_cselect_b32 s19, 1, 0
	v_writelane_b32 v247, s19, 43
	s_cbranch_vccnz .LBB0_316
	s_cmp_lt_u32 s74, 0x900
	s_cbranch_scc0 .Lpc_skip
	s_cmp_lg_u32 s73, 0
	s_cbranch_scc1 .Lpc_skip
	s_mov_b64 s[100:101], exec
	s_mov_b64 exec, 1
	s_add_u32 s20, s64, s62
	s_addc_u32 s21, s65, s63
	v_accvgpr_write_b32 a1, 1
	s_nop 4
	global_atomic_add a0, v193, a1, s[20:21] offset:256 sc0
	s_mov_b64 exec, s[100:101]
.Lpc_skip:
	s_cmp_lt_u32 s74, 1024
	s_cbranch_scc0 .Lq4_b
	s_lshr_b32 s19, s74, 6
	s_lshl_b32 s19, s19, 7
	s_and_b32 s20, s74, 63
	s_add_u32 s19, s19, s20
	s_add_u32 s74, s19, 512
	s_branch .Lq4_done

; __global__ void __launch_bounds__(512) hybrid_fwd(Params p) {
	.amdhsa_kernel _Z10hybrid_fwd6Params
		.amdhsa_group_segment_fixed_size 0
		.amdhsa_private_segment_fixed_size 0
		.amdhsa_kernarg_size 424
		.amdhsa_user_sgpr_count 2
		.amdhsa_user_sgpr_dispatch_ptr 0
		.amdhsa_user_sgpr_queue_ptr 0
		.amdhsa_user_sgpr_kernarg_segment_ptr 1
		.amdhsa_user_sgpr_dispatch_id 0
		.amdhsa_user_sgpr_kernarg_preload_length 0
		.amdhsa_user_sgpr_kernarg_preload_offset 0
		.amdhsa_user_sgpr_private_segment_size 0
		.amdhsa_uses_dynamic_stack 0
		.amdhsa_enable_private_segment 0
		.amdhsa_system_sgpr_workgroup_id_x 1
		.amdhsa_system_sgpr_workgroup_id_y 0
		.amdhsa_system_sgpr_workgroup_id_z 0
		.amdhsa_system_sgpr_workgroup_info 0
		.amdhsa_system_vgpr_workitem_id 2
		.amdhsa_next_free_vgpr 256
		.amdhsa_next_free_sgpr 102
		.amdhsa_accum_offset 252
		.amdhsa_reserve_vcc 1
		.amdhsa_float_round_mode_32 0
		.amdhsa_float_round_mode_16_64 0
		.amdhsa_float_denorm_mode_32 3
		.amdhsa_float_denorm_mode_16_64 3
		.amdhsa_dx10_clamp 1
		.amdhsa_ieee_mode 1
		.amdhsa_fp16_overflow 0
		.amdhsa_tg_split 0
		.amdhsa_exception_fp_ieee_invalid_op 0
		.amdhsa_exception_fp_denorm_src 0
		.amdhsa_exception_fp_ieee_div_zero 0
		.amdhsa_exception_fp_ieee_overflow 0
		.amdhsa_exception_fp_ieee_underflow 0
		.amdhsa_exception_fp_ieee_inexact 0
		.amdhsa_exception_int_div_zero 0
	.end_amdhsa_kernel

; __global__ void __launch_bounds__(512) hybrid_fwd(Params p) {
amdhsa.kernels:
  - .agpr_count:     4
    .args:
      - .offset:         0
        .size:           168
        .value_kind:     by_value
      - .offset:         168
        .size:           4
        .value_kind:     hidden_block_count_x
      - .offset:         172
        .size:           4
        .value_kind:     hidden_block_count_y
      - .offset:         176
        .size:           4
        .value_kind:     hidden_block_count_z
      - .offset:         180
        .size:           2
        .value_kind:     hidden_group_size_x
      - .offset:         182
        .size:           2
        .value_kind:     hidden_group_size_y
      - .offset:         184
        .size:           2
        .value_kind:     hidden_group_size_z
      - .offset:         186
        .size:           2
        .value_kind:     hidden_remainder_x
      - .offset:         188
        .size:           2
        .value_kind:     hidden_remainder_y
      - .offset:         190
        .size:           2
        .value_kind:     hidden_remainder_z
      - .offset:         208
        .size:           8
        .value_kind:     hidden_global_offset_x
      - .offset:         216
        .size:           8
        .value_kind:     hidden_global_offset_y
      - .offset:         224
        .size:           8
        .value_kind:     hidden_global_offset_z
      - .offset:         232
        .size:           2
        .value_kind:     hidden_grid_dims
      - .offset:         256
        .size:           8
        .value_kind:     hidden_multigrid_sync_arg
      - .offset:         288
        .size:           4
        .value_kind:     hidden_dynamic_lds_size
    .group_segment_fixed_size: 0
    .kernarg_segment_align: 8
    .kernarg_segment_size: 424
    .language:       OpenCL C
    .language_version:
      - 2
      - 0
    .max_flat_workgroup_size: 512
    .name:           _Z10hybrid_fwd6Params
    .private_segment_fixed_size: 0
    .sgpr_count:     108
    .sgpr_spill_count: 227
    .symbol:         _Z10hybrid_fwd6Params.kd
    .uniform_work_group_size: 1
    .uses_dynamic_stack: false
    .vgpr_count:     256
    .vgpr_spill_count: 0
    .wavefront_size: 64
